# strategy4: static s_setprio 1 for waves 4-7 during P2 conv and P7 attention/SGU phases (on top of v019)
# baseline (speedup 1.0000x reference)
; #define LAS __attribute__((address_space(3)))
; DI void phase_conv(const Params& p, LAS unsigned char* lds) {
;     const int tid = threadIdx.x, lane = tid & 63, wid = __builtin_amdgcn_readfirstlane(tid >> 6);
;     unsigned char* ws = p.ws;
;     const bf16_t* A0 = (const bf16_t*)(ws + WS_A); const bf16_t* Z0 = (const bf16_t*)(ws + WS_A + SUB); const bf16_t* GB0 = (const bf16_t*)(ws + WS_A + 2 * SUB);
;     bf16_t* CAT = (bf16_t*)(ws + WS_CAT);
;     const float* cache_a = p.in[2]; const float* cache_b = p.in[3];
;     const float* caw = p.in[8];
;     float* out = p.out;
;     const int c0 = lane * 8, par = wid >> 2;
;     __syncthreads();
.LBB0_402:
	v_readfirstlane_b32 s98, v0
	s_nop 0
	s_bfe_u32 s98, s98, 0x40006
	s_cmp_ge_u32 s98, 4
	s_cbranch_scc0 .Lprio_skip_p2
	s_setprio 1

; DI unsigned xb_add(unsigned* p, unsigned v) { return __hip_atomic_fetch_add(p, v, __ATOMIC_RELAXED, __HIP_MEMORY_SCOPE_AGENT); }
; #define SEAM(k) do { if (IN(k) && IN((k) + 1)) { xcd_barrier(xbar); } } while (0)
; DI void xcd_barrier(const XcdBarrier& b) {
;     asm volatile("s_waitcnt vmcnt(0)" ::: "memory");
;     __syncthreads();
;     if (threadIdx.x == 0) {
;         unsigned* bar = b.bar;
;         __builtin_amdgcn_s_waitcnt(0);
;         unsigned nloc = b.st[0], nx = b.st[1];
;         if (nloc == 0u) { xcd_barrier_complete(bar, b.x, nloc, nx); b.st[0] = nloc; b.st[1] = nx; }
;         const unsigned old = xb_add(&bar[XB_XSUB(b.x)], 1u);
; __global__ void __launch_bounds__(512, 2) fwd_kernel(Params p) {
;     ...
;     SEAM(2);
.LBB0_454:
	s_setprio 0
	s_cmp_gt_i32 s31, 3
	s_cselect_b64 s[0:1], -1, 0
	s_and_b64 s[4:5], s[4:5], s[0:1]
	s_andn2_b64 vcc, exec, s[4:5]
	s_cbranch_vccnz .LBB0_504
	s_waitcnt vmcnt(0)
	v_and_b32_e32 v1, 0x3ff, v0
	v_cmp_eq_u32_e32 vcc, 0, v1
	s_barrier
	s_and_saveexec_b64 s[4:5], vcc
	s_cbranch_execz .LBB0_503
	s_add_i32 s6, 0, 0x27fc0
	v_mov_b32_e32 v1, s6
	s_waitcnt vmcnt(0) expcnt(0) lgkmcnt(0)
	ds_read_b32 v3, v1
	s_add_i32 s6, 0, 0x27fc4
	v_mov_b32_e32 v1, s6
	ds_read_b32 v1, v1
	s_waitcnt lgkmcnt(1)
	v_cmp_ne_u32_e32 vcc, 0, v3
	s_cbranch_vccnz .LBB0_471
	v_readlane_b32 s6, v247, 0
	v_readlane_b32 s7, v247, 1
	s_load_dwordx2 s[10:11], s[6:7], 0x4
	s_add_u32 s6, s28, 0x1000
	s_addc_u32 s7, s29, 0
	s_add_u32 s8, s28, 0x1100
	s_addc_u32 s9, s29, 0
	s_waitcnt lgkmcnt(0)
	s_mul_i32 s33, s10, s3
	s_add_u32 s10, s28, 0x1200
	s_mul_i32 s33, s33, s11
	s_addc_u32 s11, s29, 0
	s_add_u32 s16, s28, 0x1300
	s_addc_u32 s17, s29, 0
	s_mov_b32 s54, 1
	v_mov_b32_e32 v17, 0
	s_branch .LBB0_459

; DI unsigned xb_add(unsigned* p, unsigned v) { return __hip_atomic_fetch_add(p, v, __ATOMIC_RELAXED, __HIP_MEMORY_SCOPE_AGENT); }
; #define SEAM(k) do { if (IN(k) && IN((k) + 1)) { xcd_barrier(xbar); } } while (0)
; DI void xcd_barrier(const XcdBarrier& b) {
;     asm volatile("s_waitcnt vmcnt(0)" ::: "memory");
;     __syncthreads();
;     if (threadIdx.x == 0) {
;         unsigned* bar = b.bar;
;         __builtin_amdgcn_s_waitcnt(0);
;         unsigned nloc = b.st[0], nx = b.st[1];
;         if (nloc == 0u) { xcd_barrier_complete(bar, b.x, nloc, nx); b.st[0] = nloc; b.st[1] = nx; }
;         const unsigned old = xb_add(&bar[XB_XSUB(b.x)], 1u);
; __global__ void __launch_bounds__(512, 2) fwd_kernel(Params p) {
;     ...
;     SEAM(7);
.LBB0_1269:
	s_setprio 0
	s_cmp_gt_i32 s31, 8
	s_cselect_b64 s[0:1], -1, 0
	s_and_b64 s[4:5], s[14:15], s[0:1]
	s_andn2_b64 vcc, exec, s[4:5]
	s_cbranch_vccnz .LBB0_1319
	s_waitcnt vmcnt(0)
	v_and_b32_e32 v2, 0x3ff, v0
	v_cmp_eq_u32_e32 vcc, 0, v2
	s_barrier
	s_and_saveexec_b64 s[4:5], vcc
	s_cbranch_execz .LBB0_1318
	s_add_i32 s6, 0, 0x27fc0
	v_mov_b32_e32 v2, s6
	s_waitcnt vmcnt(0) expcnt(0) lgkmcnt(0)
	ds_read_b32 v4, v2
	s_add_i32 s6, 0, 0x27fc4
	v_mov_b32_e32 v2, s6
	ds_read_b32 v2, v2
	s_waitcnt lgkmcnt(1)
	v_cmp_ne_u32_e32 vcc, 0, v4
	s_cbranch_vccnz .LBB0_1286
	v_readlane_b32 s6, v247, 0
	v_readlane_b32 s7, v247, 1
	s_load_dwordx2 s[10:11], s[6:7], 0x4
	s_add_u32 s6, s28, 0x1000
	s_addc_u32 s7, s29, 0
	s_add_u32 s8, s28, 0x1100
	s_addc_u32 s9, s29, 0
	s_waitcnt lgkmcnt(0)
	s_mul_i32 s20, s10, s3
	s_add_u32 s10, s28, 0x1200
	s_mul_i32 s20, s20, s11
	s_addc_u32 s11, s29, 0
	s_add_u32 s12, s28, 0x1300
	s_addc_u32 s13, s29, 0
	s_mov_b32 s21, 1
	v_mov_b32_e32 v18, 0
	s_branch .LBB0_1274
